# phase 5 conv rows dealt unevenly: one 4-row step for bx<192 waves, five steps for the HGRN quarter
# speedup vs baseline: 1.0091x; 1.0091x over previous
; template <int NR>
; __device__ __forceinline__ void conv_rows(const Args& a, int r0, int rstride, int lane) {
;     unsigned char* ws = a.ws; const int c0 = 8 * lane;
;     const bf16* BCp = (const bf16*)(ws + WS_BC); const bf16* CUp = (const bf16*)(ws + WS_CU);
;     v4u bq[NR], u0[NR], u1[NR], u2[NR];
; #pragma unroll
;     for (int i = 0; i < NR; ++i) { const int row = r0 + i * rstride, t = row & (SEQ - 1);
;         bq[i] = *(const v4u*)(BCp + (size_t)row * 512 + c0); u0[i] = *(const v4u*)(CUp + (size_t)row * 512 + c0);
;         u1[i] = (v4u){0, 0, 0, 0}; u2[i] = (v4u){0, 0, 0, 0};
;         if (t >= 1) u1[i] = *(const v4u*)(CUp + (size_t)(row - 1) * 512 + c0);
;         if (t >= 2) u2[i] = *(const v4u*)(CUp + (size_t)(row - 2) * 512 + c0); }
;     const float* cw = a.in[I_CONVW] + c0; const float* gn = a.in[I_CONVN] + c0;
;     const f32x4 w0a = *(const f32x4*)(cw), w0b = *(const f32x4*)(cw + 4), w1a = *(const f32x4*)(cw + 512), w1b = *(const f32x4*)(cw + 516), w2a = *(const f32x4*)(cw + 1024), w2b = *(const f32x4*)(cw + 1028);
;     const f32x4 ga = *(const f32x4*)(gn), gb = *(const f32x4*)(gn + 4);
; __global__ void __launch_bounds__(NT, 2) hymba_fwd(Args args) {
;     ...
;     if (IN(5)) _Pragma("unroll") for (int rep = 0; rep < NREP(5); ++rep) {
;         if (M % (4 * NGW) == 0) { for (int r = gw; r < M; r += 4 * NGW) conv_rows<4>(args, r, NGW, lane); } else { for (int r = gw; r < M; r += NGW) conv_rows<1>(args, r, NGW, lane); }
.Lp5_sync:
	s_waitcnt vmcnt(0) lgkmcnt(0)
	s_barrier
	s_lshl_b32 s4, s3, 5
	s_mov_b32 s98, s58
	s_movk_i32 s99, 0x4000
	s_cmpk_lg_i32 s3, 0x100
	s_cbranch_scc1 .Lp5_dealt
	s_movk_i32 s4, 0x4000
	s_cmpk_lt_u32 s2, 0xc0
	s_cbranch_scc0 .Lp5_deal_hg
	s_lshl_b32 s24, s2, 3
	s_add_i32 s24, s24, s88
	s_movk_i32 s98, 0x600
	s_movk_i32 s99, 0x1800
	s_branch .Lp5_dealt
.Lp5_deal_hg:
	s_sub_i32 s24, s2, 0xc0
	s_lshl_b32 s24, s24, 3
	s_add_i32 s24, s24, s88
	s_addk_i32 s24, 0x1800
	s_movk_i32 s98, 0x200
.Lp5_dealt:
	s_abs_i32 s6, s4
	s_waitcnt vmcnt(0)
	v_cvt_f32_u32_e32 v0, s6
	s_sub_i32 s7, 0, s6
	s_load_dwordx4 s[16:19], s[0:1], 0xa8
	v_mov_b32_e32 v97, 0
	v_rcp_iflag_f32_e32 v0, v0
	v_lshlrev_b32_e32 v96, 4, v208
	s_mov_b64 s[4:5], 0xb000000
	v_mul_f32_e32 v0, 0x4f7ffffe, v0
	v_cvt_u32_f32_e32 v2, v0
	s_waitcnt lgkmcnt(0)
	v_lshl_add_u64 v[0:1], s[18:19], 0, v[96:97]
	v_lshl_add_u64 v[98:99], v[0:1], 0, s[4:5]
	v_lshlrev_b32_e32 v0, 5, v208
	v_readfirstlane_b32 s8, v2
	s_mul_i32 s7, s7, s8
	s_mul_hi_u32 s7, s8, s7
	s_add_i32 s8, s8, s7
	s_lshr_b32 s7, s8, 18
	s_mul_i32 s7, s7, s6
	s_sub_i32 s7, 0x4000, s7
	s_sub_i32 s8, s7, s6
	s_cmp_ge_u32 s7, s6
	s_cselect_b32 s7, s8, s7
	s_sub_i32 s8, s7, s6
	s_cmp_ge_u32 s7, s6
	s_cselect_b32 s8, s8, s7
	s_cmpk_lt_i32 s24, 0x4000
	s_cselect_b64 s[6:7], -1, 0
	s_cmp_eq_u32 s8, 0
	s_load_dwordx4 s[12:15], s[0:1], 0x40
	s_load_dwordx2 s[8:9], s[0:1], 0x50
	v_mov_b32_e32 v1, v97
	s_mov_b64 s[4:5], 0x1000
	s_waitcnt lgkmcnt(0)
	v_lshl_add_u64 v[100:101], s[14:15], 0, v[0:1]
	v_lshl_add_u64 v[102:103], s[8:9], 0, v[0:1]
	v_cndmask_b32_e64 v0, 0, 1, s[6:7]
	v_lshl_add_u64 v[104:105], v[100:101], 0, s[4:5]
	v_cmp_ne_u32_e64 s[4:5], 1, v0
	s_cbranch_scc1 .LBB0_754
	s_and_b64 vcc, exec, s[4:5]
	s_cbranch_vccnz .LBB0_753
	v_mbcnt_lo_u32_b32 v0, -1, 0
	v_mbcnt_hi_u32_b32 v0, -1, v0
	v_and_b32_e32 v2, 64, v0
	v_xor_b32_e32 v1, 32, v0
	v_add_u32_e32 v2, 64, v2
	v_cmp_lt_i32_e32 vcc, v1, v2
	s_ashr_i32 s25, s24, 31
	s_lshl_b64 s[6:7], s[24:25], 11
	v_cndmask_b32_e32 v1, v0, v1, vcc
	v_lshlrev_b32_e32 v12, 2, v1
	v_xor_b32_e32 v1, 16, v0
	v_cmp_lt_i32_e32 vcc, v1, v2
	s_add_u32 s6, s18, s6
	v_mov_b32_e32 v97, 0
	v_cndmask_b32_e32 v1, v0, v1, vcc
	v_lshlrev_b32_e32 v13, 2, v1
	v_xor_b32_e32 v1, 8, v0
	v_cmp_lt_i32_e32 vcc, v1, v2
	s_addc_u32 s7, s19, s7
	s_ashr_i32 s59, s58, 31
	v_cndmask_b32_e32 v1, v0, v1, vcc
	v_lshlrev_b32_e32 v14, 2, v1
	v_xor_b32_e32 v1, 4, v0
	v_cmp_lt_i32_e32 vcc, v1, v2
	s_lshl_b64 s[8:9], s[24:25], 10
	v_mov_b32_e32 v18, 0x358637bd
	v_cndmask_b32_e32 v1, v0, v1, vcc
	v_lshlrev_b32_e32 v15, 2, v1
	v_xor_b32_e32 v1, 2, v0
	v_cmp_lt_i32_e32 vcc, v1, v2
	s_mov_b32 s10, 0x800000
	s_mov_b32 s11, s24
	v_cndmask_b32_e32 v1, v0, v1, vcc
	v_lshlrev_b32_e32 v16, 2, v1
	v_xor_b32_e32 v1, 1, v0
	v_cmp_lt_i32_e32 vcc, v1, v2
	s_nop 1
	v_cndmask_b32_e32 v0, v0, v1, vcc
	v_lshlrev_b32_e32 v17, 2, v0
	v_lshl_add_u64 v[0:1], s[6:7], 0, v[96:97]
	s_mov_b64 s[6:7], 0xe000400
	v_lshl_add_u64 v[8:9], v[0:1], 0, s[6:7]
	s_lshl_b64 s[6:7], s[58:59], 11
	s_add_u32 s8, s18, s8
	s_addc_u32 s9, s19, s9
	v_lshl_add_u64 v[0:1], s[8:9], 0, v[96:97]
	s_mov_b64 s[8:9], 0xa000000
	v_lshl_add_u64 v[10:11], v[0:1], 0, s[8:9]
	s_lshl_b64 s[8:9], s[58:59], 10
	s_branch .LBB0_748

; template <int NR>
; __device__ __forceinline__ void conv_rows(const Args& a, int r0, int rstride, int lane) {
;     ...
;     for (int i = 0; i < NR; ++i) { const int row = r0 + i * rstride, t = row & (SEQ - 1);
;         bq[i] = *(const v4u*)(BCp + (size_t)row * 512 + c0); u0[i] = *(const v4u*)(CUp + (size_t)row * 512 + c0);
;         u1[i] = (v4u){0, 0, 0, 0}; u2[i] = (v4u){0, 0, 0, 0};
;         if (t >= 1) u1[i] = *(const v4u*)(CUp + (size_t)(row - 1) * 512 + c0);
;         if (t >= 2) u2[i] = *(const v4u*)(CUp + (size_t)(row - 2) * 512 + c0); }
;     const float* cw = a.in[I_CONVW] + c0; const float* gn = a.in[I_CONVN] + c0;
;     const f32x4 w0a = *(const f32x4*)(cw), w0b = *(const f32x4*)(cw + 4), w1a = *(const f32x4*)(cw + 512), w1b = *(const f32x4*)(cw + 516), w2a = *(const f32x4*)(cw + 1024), w2b = *(const f32x4*)(cw + 1028);
;     const f32x4 ga = *(const f32x4*)(gn), gb = *(const f32x4*)(gn + 4);
; #pragma unroll
;     for (int i = 0; i < NR; ++i) { const int row = r0 + i * rstride; float y[8]; float s = 0.f;
; #pragma unroll
;         for (int j = 0; j < 8; ++j) { const int sh = (j & 1) * 16; const unsigned ub = bq[i][j >> 1], x0 = u0[i][j >> 1], x1 = u1[i][j >> 1], x2 = u2[i][j >> 1];
;             const float B = __uint_as_float(((ub >> sh) & 0xffffu) << 16), c_0 = __uint_as_float(((x0 >> sh) & 0xffffu) << 16), c_1 = __uint_as_float(((x1 >> sh) & 0xffffu) << 16), c_2 = __uint_as_float(((x2 >> sh) & 0xffffu) << 16);
;             const float k0 = j < 4 ? w0a[j & 3] : w0b[j & 3], k1 = j < 4 ? w1a[j & 3] : w1b[j & 3], k2 = j < 4 ? w2a[j & 3] : w2b[j & 3];
;             y[j] = B * (k0 * c_2 + k1 * c_1 + k2 * c_0); s += y[j] * y[j]; }
;         s = wave_sum(s); const float rs = rsqrtf(s * (1.f / 512.f) + EPS);
.LBB0_757:
	global_load_dwordx4 v[72:75], v[100:101], off offset:2064
	global_load_dwordx4 v[40:43], v[100:101], off offset:2048
	global_load_dwordx4 v[76:79], v[100:101], off offset:16
	global_load_dwordx4 v[44:47], v[100:101], off
	global_load_dwordx4 v[68:71], v[104:105], off offset:16
	global_load_dwordx4 v[36:39], v[104:105], off
	global_load_dwordx4 v[16:19], v[102:103], off offset:16
	global_load_dwordx4 v[20:23], v[102:103], off
	v_lshlrev_b32_e32 v120, 16, v3
	v_and_b32_e32 v121, 0xffff0000, v3
	v_lshlrev_b32_e32 v116, 16, v87
	v_and_b32_e32 v117, 0xffff0000, v87
	v_lshlrev_b32_e32 v118, 16, v83
	v_and_b32_e32 v119, 0xffff0000, v83
	v_lshlrev_b32_e32 v122, 16, v91
	v_and_b32_e32 v123, 0xffff0000, v91
	v_lshlrev_b32_e32 v124, 16, v86
	v_and_b32_e32 v125, 0xffff0000, v86
	v_lshlrev_b32_e32 v86, 16, v82
	v_and_b32_e32 v87, 0xffff0000, v82
	v_lshlrev_b32_e32 v82, 16, v2
	v_and_b32_e32 v83, 0xffff0000, v2
	v_lshlrev_b32_e32 v2, 16, v90
	v_and_b32_e32 v3, 0xffff0000, v90
	v_lshlrev_b32_e32 v90, 16, v85
	v_and_b32_e32 v91, 0xffff0000, v85
	v_lshlrev_b32_e32 v126, 16, v81
	v_and_b32_e32 v127, 0xffff0000, v81
	v_lshlrev_b32_e32 v128, 16, v1
	v_and_b32_e32 v129, 0xffff0000, v1
	v_lshlrev_b32_e32 v130, 16, v89
	v_and_b32_e32 v131, 0xffff0000, v89
	v_lshlrev_b32_e32 v132, 16, v84
	v_and_b32_e32 v133, 0xffff0000, v84
	v_lshlrev_b32_e32 v84, 16, v80
	v_and_b32_e32 v85, 0xffff0000, v80
	v_lshlrev_b32_e32 v80, 16, v0
	v_and_b32_e32 v81, 0xffff0000, v0
	v_lshlrev_b32_e32 v0, 16, v88
	v_and_b32_e32 v1, 0xffff0000, v88
	s_waitcnt vmcnt(13)
	v_lshlrev_b32_e32 v88, 16, v67
	v_and_b32_e32 v89, 0xffff0000, v67
	s_waitcnt vmcnt(12)
	v_lshlrev_b32_e32 v134, 16, v63
	v_and_b32_e32 v135, 0xffff0000, v63
	v_lshlrev_b32_e32 v140, 16, v66
	v_and_b32_e32 v141, 0xffff0000, v66
	v_lshlrev_b32_e32 v66, 16, v62
	v_and_b32_e32 v67, 0xffff0000, v62
	v_lshlrev_b32_e32 v62, 16, v6
	v_and_b32_e32 v63, 0xffff0000, v6
	v_lshlrev_b32_e32 v136, 16, v7
	v_and_b32_e32 v137, 0xffff0000, v7
	v_lshlrev_b32_e32 v6, 16, v94
	v_and_b32_e32 v7, 0xffff0000, v94
	v_lshlrev_b32_e32 v138, 16, v95
	v_and_b32_e32 v139, 0xffff0000, v95
	v_lshlrev_b32_e32 v94, 16, v65
	v_and_b32_e32 v95, 0xffff0000, v65
	v_and_b32_e32 v65, 0xffff0000, v60
	s_add_i32 s26, s10, s98
	s_add_i32 s26, s26, s98
	s_lshl_b64 s[4:5], s[24:25], 11
	s_add_u32 s4, s18, s4
	s_addc_u32 s5, s19, s5
	s_waitcnt vmcnt(7)
	v_pk_mul_f32 v[120:121], v[74:75], v[120:121]
	s_waitcnt vmcnt(6)
	v_pk_mul_f32 v[80:81], v[40:41], v[80:81]
	v_pk_mul_f32 v[62:63], v[72:73], v[62:63]
	s_waitcnt vmcnt(5)
	v_pk_fma_f32 v[120:121], v[78:79], v[122:123], v[120:121]
	s_waitcnt vmcnt(4)
	v_pk_fma_f32 v[0:1], v[44:45], v[0:1], v[80:81]
	v_pk_fma_f32 v[6:7], v[76:77], v[6:7], v[62:63]
	s_waitcnt vmcnt(3)
	v_pk_fma_f32 v[62:63], v[70:71], v[118:119], v[120:121]
	s_waitcnt vmcnt(2)
	v_pk_fma_f32 v[0:1], v[36:37], v[84:85], v[0:1]
	v_pk_mul_f32 v[84:85], v[62:63], v[116:117]
	v_lshlrev_b32_e32 v116, 16, v5
	v_and_b32_e32 v117, 0xffff0000, v5
	v_pk_fma_f32 v[66:67], v[68:69], v[66:67], v[6:7]
	v_lshlrev_b32_e32 v118, 16, v93
	v_and_b32_e32 v119, 0xffff0000, v93
	v_pk_mul_f32 v[116:117], v[42:43], v[116:117]
	v_pk_mul_f32 v[62:63], v[66:67], v[140:141]
	v_lshlrev_b32_e32 v66, 16, v61
	v_and_b32_e32 v67, 0xffff0000, v61
	v_pk_fma_f32 v[116:117], v[46:47], v[118:119], v[116:117]
	v_and_b32_e32 v61, 0xffff0000, v4
	v_pk_fma_f32 v[66:67], v[38:39], v[66:67], v[116:117]
	v_and_b32_e32 v5, 0xffff0000, v92
	v_pk_mul_f32 v[66:67], v[66:67], v[94:95]
	v_lshlrev_b32_e32 v94, 16, v64
	v_and_b32_e32 v95, 0xffff0000, v64
	v_lshlrev_b32_e32 v64, 16, v60
	v_lshlrev_b32_e32 v60, 16, v4
	v_lshlrev_b32_e32 v4, 16, v92
	v_pk_mul_f32 v[60:61], v[40:41], v[60:61]
	v_pk_mul_f32 v[82:83], v[72:73], v[82:83]
	v_pk_fma_f32 v[4:5], v[44:45], v[4:5], v[60:61]
	v_pk_mul_f32 v[128:129], v[42:43], v[128:129]
	v_pk_fma_f32 v[4:5], v[36:37], v[64:65], v[4:5]
	v_pk_fma_f32 v[2:3], v[76:77], v[2:3], v[82:83]
	v_pk_fma_f32 v[82:83], v[46:47], v[130:131], v[128:129]
	v_pk_mul_f32 v[0:1], v[0:1], v[132:133]
	v_pk_mul_f32 v[4:5], v[4:5], v[94:95]
	v_pk_fma_f32 v[82:83], v[38:39], v[126:127], v[82:83]
	v_mov_b32_e32 v94, v5
	v_mov_b32_e32 v95, v1
	v_pk_mul_f32 v[136:137], v[74:75], v[136:137]
	v_pk_fma_f32 v[2:3], v[68:69], v[86:87], v[2:3]
	v_pk_mul_f32 v[82:83], v[82:83], v[90:91]
	v_mov_b32_e32 v92, v4
	v_mov_b32_e32 v93, v0
	v_pk_mul_f32 v[94:95], v[94:95], v[94:95]
	v_pk_fma_f32 v[80:81], v[78:79], v[138:139], v[136:137]
	v_pk_mul_f32 v[2:3], v[2:3], v[124:125]
	v_mov_b32_e32 v60, v66
	v_mov_b32_e32 v61, v82
	v_pk_fma_f32 v[92:93], v[92:93], v[92:93], v[94:95]
	v_pk_fma_f32 v[80:81], v[70:71], v[134:135], v[80:81]
	v_pk_mul_f32 v[86:87], v[2:3], v[2:3]
	v_pk_mul_f32 v[90:91], v[62:63], v[62:63]
	v_mov_b32_e32 v64, v67
	v_mov_b32_e32 v65, v83
	v_pk_fma_f32 v[60:61], v[60:61], v[60:61], v[92:93]
	v_pk_mul_f32 v[6:7], v[80:81], v[88:89]
	v_pk_fma_f32 v[60:61], v[64:65], v[64:65], v[60:61]
	v_mov_b32_e32 v64, v90
	v_mov_b32_e32 v65, v86
	v_pk_mul_f32 v[80:81], v[84:85], v[84:85]
	v_pk_mul_f32 v[88:89], v[6:7], v[6:7]
	v_pk_add_f32 v[60:61], v[64:65], v[60:61]
	v_mov_b32_e32 v86, v91
	v_pk_add_f32 v[60:61], v[86:87], v[60:61]
	v_mov_b32_e32 v64, v88
	v_mov_b32_e32 v65, v80
	v_pk_add_f32 v[60:61], v[64:65], v[60:61]
	v_mov_b32_e32 v80, v89
	v_pk_add_f32 v[60:61], v[80:81], v[60:61]
	ds_bpermute_b32 v65, v97, v61
	ds_bpermute_b32 v64, v97, v60
	s_waitcnt lgkmcnt(0)
	v_pk_add_f32 v[60:61], v[60:61], v[64:65]
	ds_bpermute_b32 v65, v110, v61
	ds_bpermute_b32 v64, v110, v60
	s_waitcnt lgkmcnt(0)
	v_pk_add_f32 v[60:61], v[60:61], v[64:65]
	ds_bpermute_b32 v65, v111, v61
	ds_bpermute_b32 v64, v111, v60
	s_waitcnt lgkmcnt(0)
; __device__ __forceinline__ unsigned pk2(float lo, float hi) { return pg8::cvt_pk_bf16(lo, hi); }
; template <int NR>
; __device__ __forceinline__ void conv_rows(const Args& a, int r0, int rstride, int lane) {
;     ...
;     for (int i = 0; i < NR; ++i) { const int row = r0 + i * rstride; float y[8]; float s = 0.f;
; #pragma unroll
;         for (int j = 0; j < 8; ++j) { const int sh = (j & 1) * 16; const unsigned ub = bq[i][j >> 1], x0 = u0[i][j >> 1], x1 = u1[i][j >> 1], x2 = u2[i][j >> 1];
;             const float B = __uint_as_float(((ub >> sh) & 0xffffu) << 16), c_0 = __uint_as_float(((x0 >> sh) & 0xffffu) << 16), c_1 = __uint_as_float(((x1 >> sh) & 0xffffu) << 16), c_2 = __uint_as_float(((x2 >> sh) & 0xffffu) << 16);
;             const float k0 = j < 4 ? w0a[j & 3] : w0b[j & 3], k1 = j < 4 ? w1a[j & 3] : w1b[j & 3], k2 = j < 4 ? w2a[j & 3] : w2b[j & 3];
;             y[j] = B * (k0 * c_2 + k1 * c_1 + k2 * c_0); s += y[j] * y[j]; }
;         s = wave_sum(s); const float rs = rsqrtf(s * (1.f / 512.f) + EPS);
;         v4u o; o.x = pk2(y[0] * rs * ga[0], y[1] * rs * ga[1]); o.y = pk2(y[2] * rs * ga[2], y[3] * rs * ga[3]); o.z = pk2(y[4] * rs * gb[0], y[5] * rs * gb[1]); o.w = pk2(y[6] * rs * gb[2], y[7] * rs * gb[3]);
;         pg8::st_wt16((bf16*)(ws + WS_MIX) + (size_t)row * 1024 + 512 + c0, o); }
	v_pk_add_f32 v[60:61], v[60:61], v[64:65]
	ds_bpermute_b32 v65, v112, v61
	ds_bpermute_b32 v64, v112, v60
	s_waitcnt lgkmcnt(0)
	v_pk_add_f32 v[60:61], v[60:61], v[64:65]
	ds_bpermute_b32 v65, v113, v61
	ds_bpermute_b32 v64, v113, v60
	s_waitcnt lgkmcnt(0)
	v_pk_add_f32 v[60:61], v[60:61], v[64:65]
	ds_bpermute_b32 v65, v114, v61
	ds_bpermute_b32 v64, v114, v60
	s_waitcnt lgkmcnt(0)
	v_pk_add_f32 v[64:65], v[60:61], v[64:65]
	v_mov_b64_e32 v[60:61], s[8:9]
	v_pk_fma_f32 v[80:81], v[64:65], s[6:7], v[60:61] op_sel_hi:[1,0,0]
	s_nop 0
	v_mul_f32_e32 v64, 0x4b800000, v81
	v_cmp_gt_f32_e32 vcc, s22, v81
	s_nop 1
	v_cndmask_b32_e32 v64, v81, v64, vcc
	v_rsq_f32_e32 v81, v64
	v_lshl_add_u64 v[64:65], s[4:5], 0, v[106:107]
	v_mul_f32_e32 v86, 0x45800000, v81
	v_cndmask_b32_e32 v86, v81, v86, vcc
	v_pk_mul_f32 v[0:1], v[0:1], v[86:87] op_sel_hi:[1,0]
	v_pk_mul_f32 v[82:83], v[82:83], v[86:87] op_sel_hi:[1,0]
	s_waitcnt vmcnt(0)
	v_pk_mul_f32 v[0:1], v[20:21], v[0:1]
	v_pk_mul_f32 v[82:83], v[22:23], v[82:83]
	v_cvt_pk_bf16_f32 v0, v0, v1
	v_cvt_pk_bf16_f32 v1, v82, v83
	v_pk_mul_f32 v[2:3], v[2:3], v[86:87] op_sel_hi:[1,0]
	v_pk_mul_f32 v[82:83], v[84:85], v[86:87] op_sel_hi:[1,0]
	v_lshlrev_b32_e32 v84, 16, v11
	v_and_b32_e32 v85, 0xffff0000, v11
	v_pk_mul_f32 v[2:3], v[16:17], v[2:3]
	v_pk_mul_f32 v[82:83], v[18:19], v[82:83]
	v_mul_f32_e32 v81, 0x4b800000, v80
	v_cmp_gt_f32_e32 vcc, s22, v80
	v_lshlrev_b32_e32 v86, 16, v59
	v_and_b32_e32 v87, 0xffff0000, v59
	v_pk_mul_f32 v[84:85], v[74:75], v[84:85]
	v_cvt_pk_bf16_f32 v2, v2, v3
	v_cvt_pk_bf16_f32 v3, v82, v83
	v_cndmask_b32_e32 v80, v80, v81, vcc
	v_lshlrev_b32_e32 v82, 16, v51
	v_and_b32_e32 v83, 0xffff0000, v51
	v_pk_fma_f32 v[84:85], v[78:79], v[86:87], v[84:85]
	v_rsq_f32_e32 v88, v80
	v_lshlrev_b32_e32 v80, 16, v55
	v_and_b32_e32 v81, 0xffff0000, v55
	v_pk_fma_f32 v[82:83], v[70:71], v[82:83], v[84:85]
	v_lshlrev_b32_e32 v84, 16, v54
	v_and_b32_e32 v85, 0xffff0000, v54
	v_lshlrev_b32_e32 v54, 16, v50
	v_and_b32_e32 v55, 0xffff0000, v50
	v_lshlrev_b32_e32 v50, 16, v10
	v_and_b32_e32 v51, 0xffff0000, v10
	v_lshlrev_b32_e32 v10, 16, v58
	v_and_b32_e32 v11, 0xffff0000, v58
	v_pk_mul_f32 v[50:51], v[72:73], v[50:51]
	v_lshlrev_b32_e32 v86, 16, v57
	v_pk_fma_f32 v[10:11], v[76:77], v[10:11], v[50:51]
	v_and_b32_e32 v87, 0xffff0000, v57
	v_pk_fma_f32 v[10:11], v[68:69], v[54:55], v[10:11]
	v_lshlrev_b32_e32 v58, 16, v49
	v_pk_mul_f32 v[10:11], v[10:11], v[84:85]
	v_lshlrev_b32_e32 v84, 16, v9
	v_and_b32_e32 v85, 0xffff0000, v9
	v_pk_mul_f32 v[84:85], v[42:43], v[84:85]
	v_and_b32_e32 v59, 0xffff0000, v49
	v_pk_fma_f32 v[84:85], v[46:47], v[86:87], v[84:85]
	v_lshlrev_b32_e32 v54, 16, v53
	v_and_b32_e32 v55, 0xffff0000, v53
	v_pk_fma_f32 v[58:59], v[38:39], v[58:59], v[84:85]
	v_and_b32_e32 v53, 0xffff0000, v48
	v_pk_mul_f32 v[54:55], v[58:59], v[54:55]
	v_lshlrev_b32_e32 v58, 16, v52
	v_and_b32_e32 v59, 0xffff0000, v52
	v_lshlrev_b32_e32 v52, 16, v48
	v_lshlrev_b32_e32 v48, 16, v8
	v_and_b32_e32 v49, 0xffff0000, v8
	v_lshlrev_b32_e32 v8, 16, v56
	v_and_b32_e32 v9, 0xffff0000, v56
	v_pk_mul_f32 v[48:49], v[40:41], v[48:49]
	v_lshlrev_b32_e32 v56, 16, v31
	v_pk_fma_f32 v[8:9], v[44:45], v[8:9], v[48:49]
	v_lshlrev_b32_e32 v48, 16, v35
	v_pk_fma_f32 v[8:9], v[36:37], v[52:53], v[8:9]
	v_lshlrev_b32_e32 v52, 16, v15
	v_and_b32_e32 v53, 0xffff0000, v15
	v_and_b32_e32 v49, 0xffff0000, v35
	v_pk_mul_f32 v[52:53], v[74:75], v[52:53]
	v_and_b32_e32 v57, 0xffff0000, v31
	v_pk_fma_f32 v[48:49], v[78:79], v[48:49], v[52:53]
	v_and_b32_e32 v35, 0xffff0000, v14
	v_pk_fma_f32 v[48:49], v[70:71], v[56:57], v[48:49]
	v_lshlrev_b32_e32 v56, 16, v34
	v_and_b32_e32 v57, 0xffff0000, v34
	v_lshlrev_b32_e32 v34, 16, v14
	v_pk_mul_f32 v[14:15], v[72:73], v[34:35]
	v_lshlrev_b32_e32 v34, 16, v30
	v_pk_fma_f32 v[14:15], v[76:77], v[56:57], v[14:15]
	v_and_b32_e32 v35, 0xffff0000, v30
	v_pk_fma_f32 v[14:15], v[68:69], v[34:35], v[14:15]
	v_lshlrev_b32_e32 v30, 16, v26
	v_and_b32_e32 v31, 0xffff0000, v26
	v_lshlrev_b32_e32 v34, 16, v13
	v_and_b32_e32 v35, 0xffff0000, v13
	v_pk_mul_f32 v[14:15], v[14:15], v[30:31]
	v_lshlrev_b32_e32 v30, 16, v33
	v_and_b32_e32 v31, 0xffff0000, v33
	v_pk_mul_f32 v[34:35], v[42:43], v[34:35]
	v_and_b32_e32 v33, 0xffff0000, v12
	v_pk_fma_f32 v[30:31], v[46:47], v[30:31], v[34:35]
	v_lshlrev_b32_e32 v34, 16, v29
	v_and_b32_e32 v35, 0xffff0000, v29
	v_pk_fma_f32 v[30:31], v[38:39], v[34:35], v[30:31]
	v_lshlrev_b32_e32 v34, 16, v25
	v_and_b32_e32 v35, 0xffff0000, v25
	v_pk_mul_f32 v[30:31], v[30:31], v[34:35]
	v_lshlrev_b32_e32 v34, 16, v32
	v_and_b32_e32 v35, 0xffff0000, v32
	v_lshlrev_b32_e32 v32, 16, v12
	v_pk_mul_f32 v[12:13], v[40:41], v[32:33]
	v_lshlrev_b32_e32 v32, 16, v28
	v_pk_fma_f32 v[12:13], v[44:45], v[34:35], v[12:13]
	v_and_b32_e32 v33, 0xffff0000, v28
	v_pk_fma_f32 v[12:13], v[36:37], v[32:33], v[12:13]
	v_lshlrev_b32_e32 v28, 16, v24
	v_and_b32_e32 v29, 0xffff0000, v24
	v_pk_mul_f32 v[8:9], v[8:9], v[58:59]
	v_pk_mul_f32 v[12:13], v[12:13], v[28:29]
	v_mov_b32_e32 v35, v9
	v_mov_b32_e32 v34, v13
	v_mov_b32_e32 v32, v12
	v_mov_b32_e32 v33, v8
	v_pk_mul_f32 v[34:35], v[34:35], v[34:35]
	v_mov_b32_e32 v24, v30
	v_mov_b32_e32 v25, v54
	v_pk_fma_f32 v[32:33], v[32:33], v[32:33], v[34:35]
	v_pk_mul_f32 v[50:51], v[10:11], v[10:11]
	v_lshlrev_b32_e32 v58, 16, v27
	v_and_b32_e32 v59, 0xffff0000, v27
	v_pk_mul_f32 v[26:27], v[14:15], v[14:15]
	v_mov_b32_e32 v28, v31
	v_mov_b32_e32 v29, v55
	v_pk_fma_f32 v[24:25], v[24:25], v[24:25], v[32:33]
	v_pk_mul_f32 v[80:81], v[82:83], v[80:81]
	v_pk_mul_f32 v[48:49], v[48:49], v[58:59]
	v_pk_fma_f32 v[24:25], v[28:29], v[28:29], v[24:25]
	v_mov_b32_e32 v28, v26
	v_mov_b32_e32 v29, v50
	v_pk_mul_f32 v[82:83], v[80:81], v[80:81]
	v_pk_mul_f32 v[52:53], v[48:49], v[48:49]
	v_pk_add_f32 v[24:25], v[28:29], v[24:25]
	v_mov_b32_e32 v50, v27
	v_pk_add_f32 v[24:25], v[50:51], v[24:25]
	v_mov_b32_e32 v26, v52
	v_mov_b32_e32 v27, v82
	v_pk_add_f32 v[24:25], v[26:27], v[24:25]
	v_mov_b32_e32 v82, v53
	v_pk_add_f32 v[24:25], v[82:83], v[24:25]
	ds_bpermute_b32 v27, v97, v25
	ds_bpermute_b32 v26, v97, v24
	v_add_co_u32_e64 v28, s[4:5], s23, v64
	s_nop 1
	v_addc_co_u32_e64 v29, s[4:5], 0, v65, s[4:5]
	global_store_dwordx4 v[28:29], v[0:3], off offset:1024
	s_lshl_b64 s[4:5], s[10:11], 11
	s_add_u32 s4, s18, s4
	s_waitcnt lgkmcnt(0)
; __device__ __forceinline__ unsigned pk2(float lo, float hi) { return pg8::cvt_pk_bf16(lo, hi); }
; template <int NR>
; __device__ __forceinline__ void conv_rows(const Args& a, int r0, int rstride, int lane) {
;     ...
;     for (int i = 0; i < NR; ++i) { const int row = r0 + i * rstride; float y[8]; float s = 0.f;
; #pragma unroll
;         for (int j = 0; j < 8; ++j) { const int sh = (j & 1) * 16; const unsigned ub = bq[i][j >> 1], x0 = u0[i][j >> 1], x1 = u1[i][j >> 1], x2 = u2[i][j >> 1];
;             const float B = __uint_as_float(((ub >> sh) & 0xffffu) << 16), c_0 = __uint_as_float(((x0 >> sh) & 0xffffu) << 16), c_1 = __uint_as_float(((x1 >> sh) & 0xffffu) << 16), c_2 = __uint_as_float(((x2 >> sh) & 0xffffu) << 16);
;             const float k0 = j < 4 ? w0a[j & 3] : w0b[j & 3], k1 = j < 4 ? w1a[j & 3] : w1b[j & 3], k2 = j < 4 ? w2a[j & 3] : w2b[j & 3];
;             y[j] = B * (k0 * c_2 + k1 * c_1 + k2 * c_0); s += y[j] * y[j]; }
;         s = wave_sum(s); const float rs = rsqrtf(s * (1.f / 512.f) + EPS);
;         v4u o; o.x = pk2(y[0] * rs * ga[0], y[1] * rs * ga[1]); o.y = pk2(y[2] * rs * ga[2], y[3] * rs * ga[3]); o.z = pk2(y[4] * rs * gb[0], y[5] * rs * gb[1]); o.w = pk2(y[6] * rs * gb[2], y[7] * rs * gb[3]);
;         pg8::st_wt16((bf16*)(ws + WS_MIX) + (size_t)row * 1024 + 512 + c0, o); }
; __global__ void __launch_bounds__(NT, 2) hymba_fwd(Args args) {
;     ...
;         if (M % (4 * NGW) == 0) { for (int r = gw; r < M; r += 4 * NGW) conv_rows<4>(args, r, NGW, lane); } else { for (int r = gw; r < M; r += NGW) conv_rows<1>(args, r, NGW, lane); }
	v_pk_add_f32 v[2:3], v[24:25], v[26:27]
	ds_bpermute_b32 v25, v110, v3
	ds_bpermute_b32 v24, v110, v2
	v_mul_f32_e32 v0, 0x45800000, v88
	v_cndmask_b32_e32 v28, v88, v0, vcc
	v_pk_mul_f32 v[0:1], v[4:5], v[28:29] op_sel_hi:[1,0]
	v_pk_mul_f32 v[4:5], v[66:67], v[28:29] op_sel_hi:[1,0]
	s_waitcnt lgkmcnt(0)
	v_pk_add_f32 v[2:3], v[2:3], v[24:25]
	ds_bpermute_b32 v25, v111, v3
	ds_bpermute_b32 v24, v111, v2
	v_pk_mul_f32 v[0:1], v[20:21], v[0:1]
	v_pk_mul_f32 v[4:5], v[22:23], v[4:5]
	v_cvt_pk_bf16_f32 v0, v0, v1
	v_cvt_pk_bf16_f32 v1, v4, v5
	s_waitcnt lgkmcnt(0)
	v_pk_add_f32 v[24:25], v[2:3], v[24:25]
	ds_bpermute_b32 v27, v112, v25
	ds_bpermute_b32 v26, v112, v24
	v_pk_mul_f32 v[4:5], v[62:63], v[28:29] op_sel_hi:[1,0]
	s_addc_u32 s5, s19, s5
	v_pk_mul_f32 v[4:5], v[16:17], v[4:5]
	s_nop 0
	v_cvt_pk_bf16_f32 v2, v4, v5
	v_pk_mul_f32 v[4:5], v[6:7], v[28:29] op_sel_hi:[1,0]
	s_nop 0
	v_pk_mul_f32 v[4:5], v[18:19], v[4:5]
	s_nop 0
	v_cvt_pk_bf16_f32 v3, v4, v5
	s_waitcnt lgkmcnt(0)
	v_pk_add_f32 v[4:5], v[24:25], v[26:27]
	ds_bpermute_b32 v7, v113, v5
	ds_bpermute_b32 v6, v113, v4
	v_lshl_add_u64 v[24:25], s[4:5], 0, v[106:107]
	v_add_co_u32_e32 v24, vcc, s23, v24
	s_lshl_b64 s[4:5], s[14:15], 11
	s_waitcnt lgkmcnt(0)
	v_pk_add_f32 v[4:5], v[4:5], v[6:7]
	ds_bpermute_b32 v7, v114, v5
	ds_bpermute_b32 v6, v114, v4
	v_addc_co_u32_e32 v25, vcc, 0, v25, vcc
	global_store_dwordx4 v[24:25], v[0:3], off offset:1024
	s_add_u32 s4, s18, s4
	s_addc_u32 s5, s19, s5
	s_waitcnt lgkmcnt(0)
	v_pk_add_f32 v[0:1], v[4:5], v[6:7]
	v_lshl_add_u64 v[6:7], s[4:5], 0, v[106:107]
	v_pk_fma_f32 v[4:5], v[0:1], s[6:7], v[60:61] op_sel_hi:[1,0,0]
	s_nop 0
	v_mul_f32_e32 v0, 0x4b800000, v5
	v_cmp_gt_f32_e32 vcc, s22, v5
	s_nop 1
	v_cndmask_b32_e32 v0, v5, v0, vcc
	v_rsq_f32_e32 v0, v0
	v_mul_f32_e32 v5, 0x4b800000, v4
	v_mul_f32_e32 v1, 0x45800000, v0
	v_cndmask_b32_e32 v24, v0, v1, vcc
	v_pk_mul_f32 v[0:1], v[8:9], v[24:25] op_sel_hi:[1,0]
	v_pk_mul_f32 v[2:3], v[54:55], v[24:25] op_sel_hi:[1,0]
	v_pk_mul_f32 v[0:1], v[20:21], v[0:1]
	v_pk_mul_f32 v[2:3], v[22:23], v[2:3]
	v_cvt_pk_bf16_f32 v0, v0, v1
	v_cvt_pk_bf16_f32 v1, v2, v3
	v_pk_mul_f32 v[2:3], v[10:11], v[24:25] op_sel_hi:[1,0]
	v_pk_mul_f32 v[8:9], v[80:81], v[24:25] op_sel_hi:[1,0]
	v_cmp_gt_f32_e32 vcc, s22, v4
	v_pk_mul_f32 v[2:3], v[16:17], v[2:3]
	v_pk_mul_f32 v[8:9], v[18:19], v[8:9]
	v_cndmask_b32_e32 v4, v4, v5, vcc
	v_cvt_pk_bf16_f32 v2, v2, v3
	v_cvt_pk_bf16_f32 v3, v8, v9
	v_rsq_f32_e32 v8, v4
	v_add_co_u32_e64 v4, s[4:5], s23, v6
	s_nop 1
	v_addc_co_u32_e64 v5, s[4:5], 0, v7, s[4:5]
	global_store_dwordx4 v[4:5], v[0:3], off offset:1024
	s_lshl_b64 s[4:5], s[20:21], 11
	s_add_u32 s4, s18, s4
	v_mul_f32_e32 v0, 0x45800000, v8
	v_cndmask_b32_e32 v4, v8, v0, vcc
	v_pk_mul_f32 v[0:1], v[12:13], v[4:5] op_sel_hi:[1,0]
	v_pk_mul_f32 v[2:3], v[30:31], v[4:5] op_sel_hi:[1,0]
	v_pk_mul_f32 v[0:1], v[20:21], v[0:1]
	v_pk_mul_f32 v[2:3], v[22:23], v[2:3]
	v_cvt_pk_bf16_f32 v0, v0, v1
	v_cvt_pk_bf16_f32 v1, v2, v3
	v_pk_mul_f32 v[2:3], v[14:15], v[4:5] op_sel_hi:[1,0]
	v_pk_mul_f32 v[4:5], v[48:49], v[4:5] op_sel_hi:[1,0]
	v_pk_mul_f32 v[2:3], v[16:17], v[2:3]
	v_pk_mul_f32 v[4:5], v[18:19], v[4:5]
	s_addc_u32 s5, s19, s5
	v_cvt_pk_bf16_f32 v2, v2, v3
	v_cvt_pk_bf16_f32 v3, v4, v5
	v_lshl_add_u64 v[4:5], s[4:5], 0, v[106:107]
	v_add_co_u32_e32 v4, vcc, 0xe000000, v4
	s_add_i32 s24, s26, s98
	s_nop 0
	v_addc_co_u32_e32 v5, vcc, 0, v5, vcc
	s_cmp_ge_i32 s24, s99
	global_store_dwordx4 v[4:5], v[0:3], off offset:1024
	s_cbranch_scc1 .LBB0_939
